# P4 scan: next work-queue ticket fetched one unit ahead (returning atomic overlapped with the first chunk's loads)
# baseline (speedup 1.0000x reference)
.Lscan_setup:
	s_add_u32 s0, s28, 0x14500000
	v_writelane_b32 v254, s0, 50
	s_addc_u32 s0, s29, 0
	v_writelane_b32 v254, s0, 51
	s_add_u32 s0, s28, 0x3800
	s_addc_u32 s1, s29, 0
	v_writelane_b32 v254, s0, 52
	s_mov_b64 s[98:99], exec
	s_and_b64 exec, exec, s[56:57]
	s_cbranch_execz .Lq_noprime
	v_mov_b32_e32 v0, 0
	v_mov_b32_e32 v255, 1
	global_atomic_add v255, v0, v255, s[0:1] sc0
.Lq_noprime:
	s_mov_b64 exec, s[98:99]
	s_cmpk_lt_i32 s2, 0x80
	v_lshrrev_b32_e32 v111, 4, v146
	v_writelane_b32 v254, s1, 53
	s_cselect_b64 s[0:1], -1, 0
	s_and_b64 s[70:71], s[0:1], s[38:39]
	s_cmp_lt_i32 s2, 64
	s_cselect_b64 s[24:25], -1, 0
	s_lshl_b32 s87, s20, 5
	s_add_i32 s0, s87, 0
	s_add_i32 s0, s0, 0x20000
	v_lshl_add_u32 v147, v111, 3, s0
	s_movk_i32 s0, 0x100
	v_cmp_gt_i32_e64 s[6:7], s0, v108
	s_lshl_b32 s0, s20, 2
	s_and_b32 s0, s0, 4
	v_and_b32_e32 v110, 15, v108
	s_lshl_b32 s92, s0, 4
	s_lshl_b32 s94, s0, 6
	s_or_b32 s1, s0, 1
	s_or_b32 s10, s0, 2
	s_or_b32 s0, s0, 3
	v_writelane_b32 v254, s20, 54
	s_lshl_b32 s95, s1, 6
	s_lshl_b32 s97, s0, 6
	s_lshl_b32 s3, s1, 4
	s_lshl_b32 s19, s0, 4
	v_cmp_eq_u32_e64 s[0:1], 0, v110
	s_lshl_b32 s52, s20, 4
	s_ashr_i32 s53, s52, 31
	v_writelane_b32 v254, s0, 55
	s_and_b32 s86, s2, 63
	s_add_i32 s90, 0, 0x1b000
	v_writelane_b32 v254, s1, 56
	v_writelane_b32 v254, s50, 57
	s_and_b32 s91, s52, 0xffffffe0
	s_or_b32 s93, s52, 16
	v_writelane_b32 v254, s51, 58
	s_lshl_b32 s96, s10, 6
	v_readlane_b32 s36, v254, 10
	s_lshl_b32 s18, s10, 4
	s_lshl_b64 s[16:17], s[52:53], 2
	v_readlane_b32 s46, v254, 20
	v_readlane_b32 s47, v254, 21
	s_add_u32 s0, s46, s16
	v_readlane_b32 s38, v254, 12
	s_addc_u32 s1, s47, s17
	v_readlane_b32 s39, v254, 13
	s_add_u32 s38, s28, 0xe500000
	v_readlane_b32 s40, v254, 14
	s_addc_u32 s39, s29, 0
	v_readlane_b32 s41, v254, 15
	s_add_u32 s40, s28, 0xe500800
	v_or_b32_e32 v0, 48, v146
	v_readlane_b32 s42, v254, 16
	s_addc_u32 s41, s29, 0
	v_mul_u32_u24_e32 v149, 0x120, v0
	v_lshlrev_b32_e32 v0, 4, v108
	v_and_b32_e32 v8, 1, v108
	v_readlane_b32 s43, v254, 17
	s_add_u32 s42, s28, 0xe500c00
	v_mov_b32_e32 v1, 0
	v_and_b32_e32 v12, 16, v0
	v_cmp_eq_u32_e32 vcc, 0, v8
	v_lshlrev_b32_e32 v13, 4, v8
	v_lshlrev_b32_e32 v8, 3, v108
	v_and_b32_e32 v165, 0xf0, v0
	v_and_b32_e32 v166, 0x70, v0
	v_readlane_b32 s37, v254, 11
	v_readlane_b32 s50, v254, 24
	v_readlane_b32 s51, v254, 25
	v_and_b32_e32 v0, 48, v146
	s_addc_u32 s43, s29, 0
	v_and_b32_e32 v163, 0x78, v8
	v_and_b32_e32 v164, 56, v8
	v_readlane_b32 s50, v254, 57
	v_readlane_b32 s36, v254, 44
	v_lshl_add_u64 v[8:9], s[0:1], 0, v[0:1]
	s_add_u32 s0, s28, 0x145c0000
	v_readlane_b32 s44, v254, 18
	v_readlane_b32 s45, v254, 19
	v_readlane_b32 s48, v254, 22
	v_readlane_b32 s49, v254, 23
	v_readlane_b32 s51, v254, 58
	v_readlane_b32 s37, v254, 45
	v_writelane_b32 v254, s0, 59
	s_addc_u32 s0, s29, 0
	v_writelane_b32 v254, s0, 60
	v_lshlrev_b32_e32 v10, 9, v110
	v_readlane_b32 s76, v254, 0
	v_readlane_b32 s80, v254, 4
	v_readlane_b32 s81, v254, 5
	v_readlane_b32 s82, v254, 6
	v_readlane_b32 s83, v254, 7
	s_mov_b64 s[12:13], s[80:81]
	s_mov_b64 s[14:15], s[82:83]
	s_add_u32 s0, s14, s16
	v_readlane_b32 s77, v254, 1
	v_readlane_b32 s78, v254, 2
	v_readlane_b32 s79, v254, 3
	v_writelane_b32 v254, s16, 61
	s_addc_u32 s1, s15, s17
	s_add_u32 s44, s28, 0x8500400
	v_mov_b32_e32 v11, v1
	s_addc_u32 s45, s29, 0
	v_lshl_add_u64 v[122:123], v[8:9], 0, v[10:11]
	v_lshl_add_u64 v[8:9], s[0:1], 0, v[0:1]
	s_add_u32 s48, s28, 0x10500000
	v_lshlrev_b32_e32 v2, 2, v111
	v_lshl_add_u64 v[8:9], v[8:9], 0, v[10:11]
	s_mov_b64 s[0:1], 0x5010200
	s_addc_u32 s49, s29, 0
	v_lshrrev_b32_e32 v3, 1, v108
	s_movk_i32 s89, 0xa0
	v_add_u32_e32 v5, 0x400, v108
	v_or_b32_e32 v162, s52, v2
	v_lshl_add_u64 v[124:125], v[8:9], 0, s[0:1]
	s_add_u32 s0, s28, 0x8500800
	v_mul_lo_u32 v3, v3, s89
	v_add_u32_e32 v4, 0x200, v108
	v_ashrrev_i32_e32 v154, 4, v5
	v_add_u32_e32 v5, 0x600, v108
	v_lshlrev_b32_e32 v114, 8, v162
	s_addc_u32 s1, s29, 0
	s_movk_i32 s85, 0x80
	v_add_u32_e32 v3, s90, v3
	v_ashrrev_i32_e32 v150, 4, v108
	v_ashrrev_i32_e32 v152, 4, v4
	v_ashrrev_i32_e32 v156, 4, v5
	v_ashrrev_i32_e32 v158, 3, v108
	v_ashrrev_i32_e32 v160, 3, v4
	v_mov_b32_e32 v109, v1
	v_or_b32_e32 v116, 0x100, v114
	v_or_b32_e32 v118, 0x200, v114
	v_or_b32_e32 v120, 0x300, v114
	v_mov_b32_e32 v4, 0x3f80
	s_add_u32 s65, s28, 0x14500bfc
	s_mov_b32 s21, 0
	v_cmp_eq_u32_e64 s[4:5], 0, v108
	s_movk_i32 s88, 0x120
	v_mul_u32_u24_e32 v148, 0x120, v110
	v_sub_u32_e32 v151, 0x7f, v150
	v_sub_u32_e32 v153, 0x7f, v152
	v_sub_u32_e32 v155, 0x7f, v154
	v_sub_u32_e32 v157, 0x7f, v156
	v_sub_u32_e32 v159, 0x7f, v158
	v_sub_u32_e32 v161, 0x7f, v160
	v_cmp_gt_i32_e64 s[8:9], s85, v108
	v_mov_b64_e32 v[112:113], v[108:109]
	v_ashrrev_i32_e32 v109, 31, v108
	v_cndmask_b32_e32 v4, 0, v4, vcc
	v_mov_b32_e32 v5, v1
	v_mov_b32_e32 v6, v1
	v_mov_b32_e32 v7, v1
	v_ashrrev_i32_e32 v115, 31, v114
	v_ashrrev_i32_e32 v117, 31, v116
	v_ashrrev_i32_e32 v119, 31, v118
	v_ashrrev_i32_e32 v121, 31, v120
	s_addc_u32 s84, s29, 0
	s_add_i32 s35, 0, 0x27fe0
	v_add_u32_e32 v167, v3, v12
	s_add_i32 s10, 0, 0x26600
	v_mov_b32_e32 v168, 0x145c0000
	v_add_u32_e32 v169, v3, v13
	s_movk_i32 s11, 0x1800
	v_mov_b32_e32 v170, 0x3db504f3
	v_lshlrev_b32_e32 v126, 2, v2
	v_mov_b32_e32 v171, 0x5010000
	v_mov_b32_e32 v186, v1
	v_mov_b32_e32 v187, v1
	v_mov_b32_e32 v188, v1
	v_mov_b32_e32 v189, v1
	v_mbcnt_hi_u32_b32 v172, -1, v185
	s_mov_b32 s68, 0
	s_mov_b32 s69, s2
	v_writelane_b32 v254, s17, 62
	s_branch .LBB0_577

.LBB0_580:
	s_mov_b32 s16, 2
	s_and_b64 vcc, exec, s[78:79]
	s_cbranch_vccz .LBB0_589
	s_xor_b64 s[16:17], s[70:71], -1
	s_mov_b64 s[74:75], -1
	s_and_b64 vcc, exec, s[16:17]
	s_mov_b32 s17, s86
	s_mov_b64 s[76:77], s[24:25]
	s_mov_b64 s[46:47], -1
	s_cbranch_vccz .LBB0_590
	s_barrier
	s_and_saveexec_b64 s[46:47], s[4:5]
	s_cbranch_execz .LBB0_586
	s_mov_b64 s[74:75], exec
	v_mbcnt_lo_u32_b32 v0, s74, 0
	v_mbcnt_hi_u32_b32 v0, s75, v0
	v_cmp_eq_u32_e32 vcc, 0, v0
	s_and_saveexec_b64 s[70:71], vcc
	s_cbranch_execz .LBB0_585
	s_waitcnt vmcnt(0)
	v_mov_b32_e32 v2, v255
	v_mov_b32_e32 v255, 1
	v_readlane_b32 s16, v254, 52
	v_readlane_b32 s17, v254, 53
	s_nop 4
	global_atomic_add v255, v1, v255, s[16:17] sc0
.LBB0_585:
	s_or_b64 exec, exec, s[70:71]
	s_nop 0
	v_readfirstlane_b32 s16, v2
	v_mov_b32_e32 v2, s35
	s_nop 0
	v_add_u32_e32 v0, s16, v0
	ds_write_b32 v2, v0

	.amdhsa_kernel _Z10fwd_kernel4Args
		.amdhsa_group_segment_fixed_size 0
		.amdhsa_private_segment_fixed_size 0
		.amdhsa_kernarg_size 488
		.amdhsa_user_sgpr_count 2
		.amdhsa_user_sgpr_dispatch_ptr 0
		.amdhsa_user_sgpr_queue_ptr 0
		.amdhsa_user_sgpr_kernarg_segment_ptr 1
		.amdhsa_user_sgpr_dispatch_id 0
		.amdhsa_user_sgpr_kernarg_preload_length 0
		.amdhsa_user_sgpr_kernarg_preload_offset 0
		.amdhsa_user_sgpr_private_segment_size 0
		.amdhsa_uses_dynamic_stack 0
		.amdhsa_enable_private_segment 0
		.amdhsa_system_sgpr_workgroup_id_x 1
		.amdhsa_system_sgpr_workgroup_id_y 0
		.amdhsa_system_sgpr_workgroup_id_z 0
		.amdhsa_system_sgpr_workgroup_info 0
		.amdhsa_system_vgpr_workitem_id 2
		.amdhsa_next_free_vgpr 256
		.amdhsa_next_free_sgpr 102
		.amdhsa_accum_offset 256
		.amdhsa_reserve_vcc 1
		.amdhsa_float_round_mode_32 0
		.amdhsa_float_round_mode_16_64 0
		.amdhsa_float_denorm_mode_32 3
		.amdhsa_float_denorm_mode_16_64 3
		.amdhsa_dx10_clamp 1
		.amdhsa_ieee_mode 1
		.amdhsa_fp16_overflow 0
		.amdhsa_tg_split 0
		.amdhsa_exception_fp_ieee_invalid_op 0
		.amdhsa_exception_fp_denorm_src 0
		.amdhsa_exception_fp_ieee_div_zero 0
		.amdhsa_exception_fp_ieee_overflow 0
		.amdhsa_exception_fp_ieee_underflow 0
		.amdhsa_exception_fp_ieee_inexact 0
		.amdhsa_exception_int_div_zero 0
	.end_amdhsa_kernel

amdhsa.kernels:
  - .agpr_count:     0
    .args:
      - .offset:         0
        .size:           232
        .value_kind:     by_value
      - .offset:         232
        .size:           4
        .value_kind:     hidden_block_count_x
      - .offset:         236
        .size:           4
        .value_kind:     hidden_block_count_y
      - .offset:         240
        .size:           4
        .value_kind:     hidden_block_count_z
      - .offset:         244
        .size:           2
        .value_kind:     hidden_group_size_x
      - .offset:         246
        .size:           2
        .value_kind:     hidden_group_size_y
      - .offset:         248
        .size:           2
        .value_kind:     hidden_group_size_z
      - .offset:         250
        .size:           2
        .value_kind:     hidden_remainder_x
      - .offset:         252
        .size:           2
        .value_kind:     hidden_remainder_y
      - .offset:         254
        .size:           2
        .value_kind:     hidden_remainder_z
      - .offset:         272
        .size:           8
        .value_kind:     hidden_global_offset_x
      - .offset:         280
        .size:           8
        .value_kind:     hidden_global_offset_y
      - .offset:         288
        .size:           8
        .value_kind:     hidden_global_offset_z
      - .offset:         296
        .size:           2
        .value_kind:     hidden_grid_dims
      - .offset:         320
        .size:           8
        .value_kind:     hidden_multigrid_sync_arg
      - .offset:         352
        .size:           4
        .value_kind:     hidden_dynamic_lds_size
    .group_segment_fixed_size: 0
    .kernarg_segment_align: 8
    .kernarg_segment_size: 488
    .language:       OpenCL C
    .language_version:
      - 2
      - 0
    .max_flat_workgroup_size: 512
    .name:           _Z10fwd_kernel4Args
    .private_segment_fixed_size: 0
    .sgpr_count:     108
    .sgpr_spill_count: 65
    .symbol:         _Z10fwd_kernel4Args.kd
    .uniform_work_group_size: 1
    .uses_dynamic_stack: false
    .vgpr_count:     256
    .vgpr_spill_count: 0
    .wavefront_size: 64
